# 64-bit accumulator zeroing in P1/P5; q/k epilogue waits moved ahead of the masked partial-sum stores (on top of gates layout + P5/P6 full-line epilogues)
# speedup vs baseline: 1.0350x; 1.0037x over previous
.LBB0_148:
	s_ashr_i32 s63, s62, 31
	s_lshl_b64 s[68:69], s[62:63], 19
	s_add_u32 s68, s55, s68
	s_addc_u32 s69, s78, s69
	s_and_b64 s[10:11], s[10:11], exec
	s_cselect_b32 s63, s69, s73
	s_cselect_b32 s65, s68, s72
	s_add_u32 s10, s74, 0x40080
	s_addc_u32 s11, s75, 0
	s_add_u32 s71, s72, 0x100
	s_addc_u32 s76, s73, 0
	s_mov_b32 s77, -2
	v_mov_b64_e32 v[32:33], 0
	v_mov_b64_e32 v[34:35], 0
	v_mov_b64_e32 v[36:37], 0
	v_mov_b64_e32 v[38:39], 0
	v_mov_b64_e32 v[40:41], 0
	v_mov_b64_e32 v[42:43], 0
	v_mov_b64_e32 v[44:45], 0
	v_mov_b64_e32 v[46:47], 0
	v_mov_b64_e32 v[48:49], 0
	v_mov_b64_e32 v[50:51], 0
	v_mov_b64_e32 v[52:53], 0
	v_mov_b64_e32 v[54:55], 0
	v_mov_b64_e32 v[56:57], 0
	v_mov_b64_e32 v[58:59], 0
	v_mov_b64_e32 v[60:61], 0
	v_mov_b64_e32 v[62:63], 0
	v_mov_b64_e32 v[64:65], 0
	v_mov_b64_e32 v[66:67], 0
	v_mov_b64_e32 v[68:69], 0
	v_mov_b64_e32 v[70:71], 0
	v_mov_b64_e32 v[72:73], 0
	v_mov_b64_e32 v[74:75], 0
	v_mov_b64_e32 v[76:77], 0
	v_mov_b64_e32 v[78:79], 0
	v_mov_b64_e32 v[80:81], 0
	v_mov_b64_e32 v[82:83], 0
	v_mov_b64_e32 v[84:85], 0
	v_mov_b64_e32 v[86:87], 0
	v_mov_b64_e32 v[88:89], 0
	v_mov_b64_e32 v[90:91], 0
	v_mov_b64_e32 v[92:93], 0
	v_mov_b64_e32 v[94:95], 0
	v_mov_b64_e32 v[96:97], 0
	v_mov_b64_e32 v[98:99], 0
	v_mov_b64_e32 v[100:101], 0
	v_mov_b64_e32 v[102:103], 0
	v_mov_b64_e32 v[104:105], 0
	v_mov_b64_e32 v[106:107], 0
	v_mov_b64_e32 v[108:109], 0
	v_mov_b64_e32 v[110:111], 0
	v_mov_b64_e32 v[112:113], 0
	v_mov_b64_e32 v[114:115], 0
	v_mov_b64_e32 v[116:117], 0
	v_mov_b64_e32 v[118:119], 0
	v_mov_b64_e32 v[120:121], 0
	v_mov_b64_e32 v[122:123], 0
	v_mov_b64_e32 v[124:125], 0
	v_mov_b64_e32 v[126:127], 0
	v_mov_b64_e32 v[128:129], 0
	v_mov_b64_e32 v[130:131], 0
	v_mov_b64_e32 v[132:133], 0
	v_mov_b64_e32 v[134:135], 0
	v_mov_b64_e32 v[136:137], 0
	v_mov_b64_e32 v[138:139], 0
	v_mov_b64_e32 v[140:141], 0
	v_mov_b64_e32 v[142:143], 0
	v_mov_b64_e32 v[144:145], 0
	v_mov_b64_e32 v[146:147], 0
	v_mov_b64_e32 v[148:149], 0
	v_mov_b64_e32 v[150:151], 0
	v_mov_b64_e32 v[152:153], 0
	v_mov_b64_e32 v[154:155], 0
	v_mov_b64_e32 v[156:157], 0
	v_mov_b64_e32 v[158:159], 0

.LBB0_169:
	v_pk_mul_f32 v[158:159], v[158:159], s[54:55] op_sel_hi:[1,0]
	v_pk_mul_f32 v[196:197], v[156:157], s[54:55] op_sel_hi:[1,0]
	v_pk_mul_f32 v[198:199], v[152:153], s[54:55] op_sel_hi:[1,0]
	v_mul_f32_e32 v152, v197, v197
	v_mul_f32_e32 v153, v159, v159
	v_fmac_f32_e32 v152, v196, v196
	v_fmac_f32_e32 v153, v158, v158
	v_and_b32_e32 v193, 64, v217
	v_add_f32_e32 v152, v152, v153
	v_mul_f32_e32 v153, v199, v199
	v_xor_b32_e32 v178, 16, v217
	v_add_u32_e32 v193, 64, v193
	v_pk_mul_f32 v[194:195], v[154:155], s[54:55] op_sel_hi:[1,0]
	v_fmac_f32_e32 v153, v198, v198
	v_cmp_lt_i32_e32 vcc, v178, v193
	v_add_f32_e32 v152, v152, v153
	v_mul_f32_e32 v153, v195, v195
	v_cndmask_b32_e32 v178, v217, v178, vcc
	v_fmac_f32_e32 v153, v194, v194
	v_lshlrev_b32_e32 v218, 2, v178
	v_add_f32_e32 v152, v153, v152
	ds_bpermute_b32 v153, v218, v152
	v_xor_b32_e32 v178, 32, v217
	v_cmp_lt_i32_e32 vcc, v178, v193
	s_and_b64 s[76:77], s[74:75], exec
	v_ashrrev_i32_e32 v193, 31, v192
	v_cndmask_b32_e32 v178, v217, v178, vcc
	v_lshlrev_b32_e32 v219, 2, v178
	s_waitcnt lgkmcnt(0)
	v_add_f32_e32 v152, v152, v153
	ds_bpermute_b32 v153, v219, v152
	s_cselect_b32 s76, 16, 0
	v_lshlrev_b64 v[156:157], 5, v[192:193]
	s_lshl_b32 s38, s70, 1
	v_or_b32_e32 v221, s76, v156
	s_and_b32 s65, s38, 14
	s_waitcnt vmcnt(0)
	s_and_saveexec_b64 s[70:71], s[6:7]
	s_cbranch_execz .LBB0_171
	v_or_b32_e32 v156, s65, v221
	s_waitcnt lgkmcnt(0)
	v_add_f32_e32 v154, v152, v153
	v_lshl_add_u64 v[152:153], v[156:157], 4, s[40:41]
	global_store_dword v[152:153], v154, off
.LBB0_171:
	s_or_b64 exec, exec, s[70:71]
	s_and_b64 s[70:71], s[74:75], exec
	s_mov_b32 s38, 0x8a00000
	s_cselect_b32 s38, s38, 0x8200000
	s_add_u32 s38, s30, s38
	s_addc_u32 s63, s31, 0
	s_lshl_b64 s[70:71], s[72:73], 1
	s_add_u32 s70, s38, s70
	s_addc_u32 s71, s63, s71
	v_lshlrev_b32_e32 v178, 1, v180
	v_mul_f32_e32 v156, v196, v0
	v_mul_f32_e32 v196, v159, v5
	s_waitcnt lgkmcnt(0)
	v_lshl_add_u64 v[152:153], s[70:71], 0, v[178:179]
	v_mul_f32_e32 v178, v197, v4
	v_mul_f32_e32 v158, v158, v1
	v_pk_mul_f32 v[196:197], v[196:197], v[166:167] op_sel:[0,1] op_sel_hi:[0,0]
	v_pk_mul_f32 v[226:227], v[178:179], v[164:165] op_sel:[0,1] op_sel_hi:[0,0]
	v_pk_fma_f32 v[230:231], v[158:159], v[166:167], v[196:197] neg_lo:[0,0,1] neg_hi:[0,0,1]
	v_pk_fma_f32 v[158:159], v[158:159], v[166:167], v[196:197] op_sel_hi:[0,1,1]
	v_pk_mul_f32 v[150:151], v[150:151], s[54:55] op_sel_hi:[1,0]
	v_pk_mul_f32 v[148:149], v[148:149], s[54:55] op_sel_hi:[1,0]
	v_pk_fma_f32 v[228:229], v[156:157], v[164:165], v[226:227] neg_lo:[0,0,1] neg_hi:[0,0,1]
	v_pk_fma_f32 v[226:227], v[156:157], v[164:165], v[226:227] op_sel_hi:[0,1,1]
	v_mul_f32_e32 v156, v149, v149
	v_mul_f32_e32 v158, v151, v151
	v_pk_mul_f32 v[144:145], v[144:145], s[54:55] op_sel_hi:[1,0]
	v_fmac_f32_e32 v156, v148, v148
	v_fmac_f32_e32 v158, v150, v150
	v_add_f32_e32 v156, v156, v158
	v_mul_f32_e32 v158, v145, v145
	v_pk_mul_f32 v[146:147], v[146:147], s[54:55] op_sel_hi:[1,0]
	v_fmac_f32_e32 v158, v144, v144
	v_add_f32_e32 v156, v156, v158
	v_mul_f32_e32 v158, v147, v147
	v_fmac_f32_e32 v158, v146, v146
	v_add_f32_e32 v156, v158, v156
	ds_bpermute_b32 v158, v218, v156
	v_mul_f32_e32 v222, v199, v6
	v_mul_f32_e32 v198, v198, v2
	v_mul_f32_e32 v224, v195, v7
	v_pk_mul_f32 v[196:197], v[222:223], v[160:161] op_sel:[0,1] op_sel_hi:[0,0]
	s_waitcnt lgkmcnt(0)
	v_add_f32_e32 v156, v156, v158
	ds_bpermute_b32 v158, v219, v156
	v_lshlrev_b64 v[154:155], 12, v[192:193]
	v_mul_f32_e32 v194, v194, v3
	v_pk_fma_f32 v[222:223], v[198:199], v[160:161], v[196:197] neg_lo:[0,0,1] neg_hi:[0,0,1]
	v_pk_fma_f32 v[196:197], v[198:199], v[160:161], v[196:197] op_sel_hi:[0,1,1]
	v_pk_mul_f32 v[198:199], v[224:225], v[162:163] op_sel:[0,1] op_sel_hi:[0,0]
	v_lshl_add_u64 v[154:155], v[152:153], 0, v[154:155]
	v_pk_fma_f32 v[224:225], v[194:195], v[162:163], v[198:199] neg_lo:[0,0,1] neg_hi:[0,0,1]
	v_pk_fma_f32 v[198:199], v[194:195], v[162:163], v[198:199] op_sel_hi:[0,1,1]
	s_lshl_b32 s38, s65, 8
	v_cvt_pk_bf16_f32 v194, v228, v227
	v_cvt_pk_bf16_f32 v195, v230, v159
	v_cvt_pk_bf16_f32 v196, v222, v197
	v_cvt_pk_bf16_f32 v197, v224, v199
	v_lshl_add_u64 v[198:199], v[154:155], 0, s[38:39]
	s_or_b32 s63, s65, 1
	global_store_dwordx4 v[198:199], v[194:197], off
	s_and_saveexec_b64 s[70:71], s[6:7]
	s_cbranch_execz .LBB0_173
	s_waitcnt lgkmcnt(0)
	v_add_f32_e32 v158, v156, v158
	v_or_b32_e32 v156, s63, v221
	v_lshl_add_u64 v[156:157], v[156:157], 4, s[40:41]
	global_store_dword v[156:157], v158, off

.LBB0_193:
	v_pk_mul_f32 v[94:95], v[94:95], s[54:55] op_sel_hi:[1,0]
	v_pk_mul_f32 v[104:105], v[92:93], s[54:55] op_sel_hi:[1,0]
	v_pk_mul_f32 v[106:107], v[88:89], s[54:55] op_sel_hi:[1,0]
	v_mul_f32_e32 v88, v105, v105
	v_mul_f32_e32 v89, v95, v95
	v_fmac_f32_e32 v88, v104, v104
	v_fmac_f32_e32 v89, v94, v94
	v_add_f32_e32 v88, v88, v89
	v_mul_f32_e32 v89, v107, v107
	v_pk_mul_f32 v[92:93], v[90:91], s[54:55] op_sel_hi:[1,0]
	v_fmac_f32_e32 v89, v106, v106
	v_add_f32_e32 v88, v88, v89
	v_mul_f32_e32 v89, v93, v93
	v_fmac_f32_e32 v89, v92, v92
	v_add_f32_e32 v88, v89, v88
	ds_bpermute_b32 v89, v218, v88
	s_waitcnt lgkmcnt(0)
	v_add_f32_e32 v109, v88, v89
	ds_bpermute_b32 v110, v219, v109
	v_add_u32_e32 v88, 0x80, v192
	v_ashrrev_i32_e32 v89, 31, v88
	v_lshlrev_b64 v[90:91], 5, v[88:89]
	v_or_b32_e32 v108, s76, v90
	s_waitcnt vmcnt(0)
	s_and_saveexec_b64 s[10:11], s[6:7]
	s_cbranch_execz .LBB0_195
	v_or_b32_e32 v90, s65, v108
	s_waitcnt lgkmcnt(0)
	v_add_f32_e32 v109, v109, v110
	v_lshl_add_u64 v[110:111], v[90:91], 4, s[40:41]
	global_store_dword v[110:111], v109, off
.LBB0_195:
	s_or_b64 exec, exec, s[10:11]
	s_waitcnt lgkmcnt(0)
	v_mul_f32_e32 v110, v95, v5
	v_mul_f32_e32 v94, v94, v1
	v_mul_f32_e32 v112, v107, v6
	v_pk_mul_f32 v[110:111], v[110:111], v[102:103] op_sel:[0,1] op_sel_hi:[0,0]
	v_mul_f32_e32 v90, v104, v0
	v_mul_f32_e32 v104, v105, v4
	v_mul_f32_e32 v106, v106, v2
	v_mul_f32_e32 v114, v93, v7
	v_pk_fma_f32 v[118:119], v[94:95], v[102:103], v[110:111] neg_lo:[0,0,1] neg_hi:[0,0,1]
	v_pk_fma_f32 v[94:95], v[94:95], v[102:103], v[110:111] op_sel_hi:[0,1,1]
	v_pk_mul_f32 v[110:111], v[112:113], v[96:97] op_sel:[0,1] op_sel_hi:[0,0]
	v_lshlrev_b64 v[88:89], 12, v[88:89]
	v_mul_f32_e32 v92, v92, v3
	v_pk_mul_f32 v[104:105], v[104:105], v[100:101] op_sel:[0,1] op_sel_hi:[0,0]
	v_pk_fma_f32 v[112:113], v[106:107], v[96:97], v[110:111] neg_lo:[0,0,1] neg_hi:[0,0,1]
	v_pk_fma_f32 v[106:107], v[106:107], v[96:97], v[110:111] op_sel_hi:[0,1,1]
	v_pk_mul_f32 v[110:111], v[114:115], v[98:99] op_sel:[0,1] op_sel_hi:[0,0]
	v_lshl_add_u64 v[88:89], v[152:153], 0, v[88:89]
	v_pk_fma_f32 v[116:117], v[90:91], v[100:101], v[104:105] neg_lo:[0,0,1] neg_hi:[0,0,1]
	v_pk_fma_f32 v[104:105], v[90:91], v[100:101], v[104:105] op_sel_hi:[0,1,1]
	v_pk_fma_f32 v[114:115], v[92:93], v[98:99], v[110:111] neg_lo:[0,0,1] neg_hi:[0,0,1]
	v_pk_fma_f32 v[110:111], v[92:93], v[98:99], v[110:111] op_sel_hi:[0,1,1]
	v_cvt_pk_bf16_f32 v92, v116, v105
	v_cvt_pk_bf16_f32 v93, v118, v95
	v_cvt_pk_bf16_f32 v94, v112, v107
	v_cvt_pk_bf16_f32 v95, v114, v111
	v_lshl_add_u64 v[104:105], v[88:89], 0, s[38:39]
	v_pk_mul_f32 v[86:87], v[86:87], s[54:55] op_sel_hi:[1,0]
	v_pk_mul_f32 v[84:85], v[84:85], s[54:55] op_sel_hi:[1,0]
	global_store_dwordx4 v[104:105], v[92:95], off
	v_mul_f32_e32 v90, v85, v85
	v_pk_mul_f32 v[80:81], v[80:81], s[54:55] op_sel_hi:[1,0]
	v_mul_f32_e32 v92, v87, v87
	v_fmac_f32_e32 v90, v84, v84
	v_fmac_f32_e32 v92, v86, v86
	v_add_f32_e32 v90, v90, v92
	v_mul_f32_e32 v92, v81, v81
	v_pk_mul_f32 v[82:83], v[82:83], s[54:55] op_sel_hi:[1,0]
	v_fmac_f32_e32 v92, v80, v80
	v_add_f32_e32 v90, v90, v92
	v_mul_f32_e32 v92, v83, v83
	v_fmac_f32_e32 v92, v82, v82
	v_add_f32_e32 v90, v92, v90
	ds_bpermute_b32 v92, v218, v90
	s_waitcnt lgkmcnt(0)
	v_add_f32_e32 v90, v90, v92
	ds_bpermute_b32 v92, v219, v90
	s_and_saveexec_b64 s[10:11], s[6:7]
	s_cbranch_execz .LBB0_197
	s_waitcnt lgkmcnt(0)
	v_add_f32_e32 v92, v90, v92
	v_or_b32_e32 v90, s63, v108
	v_lshl_add_u64 v[90:91], v[90:91], 4, s[40:41]
	global_store_dword v[90:91], v92, off

.LBB0_446:
	s_ashr_i32 s19, s18, 31
	s_lshl_b64 s[20:21], s[18:19], 20
	s_add_u32 s17, s62, s20
	s_addc_u32 s19, s63, s21
	s_ashr_i32 s20, s18, 3
	s_ashr_i32 s21, s20, 31
	s_lshl_b64 s[20:21], s[20:21], 25
	s_add_u32 s20, s17, s20
	s_addc_u32 s21, s19, s21
	s_and_b64 s[26:27], s[6:7], exec
	s_cselect_b32 s19, s21, s37
	s_cselect_b32 s65, s20, s36
	s_ashr_i32 s17, s16, 31
	s_lshl_b64 s[26:27], s[16:17], 20
	s_add_u32 s26, s5, s26
	s_addc_u32 s27, s42, s27
	s_and_b64 s[40:41], s[6:7], exec
	s_cselect_b32 s17, s27, s39
	s_cselect_b32 s66, s26, s38
	s_add_u32 s36, s36, 0x80080
	s_addc_u32 s37, s37, 0
	s_add_u32 s67, s38, 0x100
	s_addc_u32 s68, s39, 0
	s_mov_b32 s69, -2
	v_mov_b64_e32 v[0:1], 0
	v_mov_b64_e32 v[2:3], 0
	v_mov_b64_e32 v[4:5], 0
	v_mov_b64_e32 v[6:7], 0
	v_mov_b64_e32 v[8:9], 0
	v_mov_b64_e32 v[10:11], 0
	v_mov_b64_e32 v[12:13], 0
	v_mov_b64_e32 v[14:15], 0
	v_mov_b64_e32 v[16:17], 0
	v_mov_b64_e32 v[18:19], 0
	v_mov_b64_e32 v[20:21], 0
	v_mov_b64_e32 v[22:23], 0
	v_mov_b64_e32 v[24:25], 0
	v_mov_b64_e32 v[26:27], 0
	v_mov_b64_e32 v[28:29], 0
	v_mov_b64_e32 v[30:31], 0
	v_mov_b64_e32 v[32:33], 0
	v_mov_b64_e32 v[34:35], 0
	v_mov_b64_e32 v[36:37], 0
	v_mov_b64_e32 v[38:39], 0
	v_mov_b64_e32 v[40:41], 0
	v_mov_b64_e32 v[42:43], 0
	v_mov_b64_e32 v[44:45], 0
	v_mov_b64_e32 v[46:47], 0
	v_mov_b64_e32 v[48:49], 0
	v_mov_b64_e32 v[50:51], 0
	v_mov_b64_e32 v[52:53], 0
	v_mov_b64_e32 v[54:55], 0
	v_mov_b64_e32 v[56:57], 0
	v_mov_b64_e32 v[58:59], 0
	v_mov_b64_e32 v[60:61], 0
	v_mov_b64_e32 v[62:63], 0
	v_mov_b64_e32 v[64:65], 0
	v_mov_b64_e32 v[66:67], 0
	v_mov_b64_e32 v[68:69], 0
	v_mov_b64_e32 v[70:71], 0
	v_mov_b64_e32 v[72:73], 0
	v_mov_b64_e32 v[74:75], 0
	v_mov_b64_e32 v[76:77], 0
	v_mov_b64_e32 v[78:79], 0
	v_mov_b64_e32 v[80:81], 0
	v_mov_b64_e32 v[82:83], 0
	v_mov_b64_e32 v[84:85], 0
	v_mov_b64_e32 v[86:87], 0
	v_mov_b64_e32 v[88:89], 0
	v_mov_b64_e32 v[90:91], 0
	v_mov_b64_e32 v[92:93], 0
	v_mov_b64_e32 v[94:95], 0
	v_mov_b64_e32 v[96:97], 0
	v_mov_b64_e32 v[98:99], 0
	v_mov_b64_e32 v[100:101], 0
	v_mov_b64_e32 v[102:103], 0
	v_mov_b64_e32 v[104:105], 0
	v_mov_b64_e32 v[106:107], 0
	v_mov_b64_e32 v[108:109], 0
	v_mov_b64_e32 v[110:111], 0
	v_mov_b64_e32 v[112:113], 0
	v_mov_b64_e32 v[114:115], 0
	v_mov_b64_e32 v[116:117], 0
	v_mov_b64_e32 v[118:119], 0
	v_mov_b64_e32 v[120:121], 0
	v_mov_b64_e32 v[122:123], 0
	v_mov_b64_e32 v[124:125], 0
	v_mov_b64_e32 v[126:127], 0
